# GEMM accumulator clears via 64-bit moves; layer-0 projection epilogue drops the zero-bias adds (cvt order fixed up)
# baseline (speedup 1.0000x reference)
; template <class Epi, class Sched, bool ALIGN_EPI = false, bool SP2 = false>
; __device__ __forceinline__ void gemm_phase(PG8_LAS unsigned char* lds, const Gemm g, const Sched& S, const Epi& E) {
;     ...
;         const bool has_next = S.next(ui + 1, nxt);
;         const char* nA = has_next ? (const char*)g.A + (size_t)nxt.pm * tstep : cA; const char* nB = has_next ? (const char*)g.Bt + (size_t)nxt.pn * tstep : cB;
;     ...
; #pragma unroll
;         for (int a = 0; a < 2; ++a)
; #pragma unroll
;             for (int b = 0; b < 2; ++b)
; #pragma unroll
;                 for (int m = 0; m < 4; ++m)
; #pragma unroll
;                     for (int n = 0; n < 2; ++n) acc[a][b][m][n] = (f32x4){0.f, 0.f, 0.f, 0.f};
;         cur = nxt; cA = nA; cB = nB; ++ui;
.LBB0_156:
	s_ashr_i32 s45, s44, 31
	s_lshl_b64 s[16:17], s[44:45], 19
	s_add_u32 s50, s12, s16
	s_addc_u32 s51, s13, s17
	s_and_b64 s[16:17], s[36:37], exec
	s_cselect_b32 s45, s51, s77
	s_cselect_b32 vcc_lo, s50, s76
	s_ashr_i32 s43, s42, 31
	s_lshl_b64 s[16:17], s[42:43], 19
	s_add_u32 s70, s48, s16
	s_addc_u32 s71, s49, s17
	s_and_b64 s[16:17], s[36:37], exec
	s_cselect_b32 s43, s71, s85
	s_cselect_b32 vcc_hi, s70, s84
	s_add_u32 s76, s76, 0x40080
	s_addc_u32 s77, s77, 0
	s_add_u32 s5, s84, 0x100
	v_mov_b32_e32 v0, 0
	s_addc_u32 s33, s85, 0
	s_mov_b32 s16, -2
	v_mov_b32_e32 v1, v0
	v_mov_b64_e32 v[2:3], 0
	v_mov_b64_e32 v[4:5], 0
	v_mov_b64_e32 v[6:7], 0
	v_mov_b64_e32 v[12:13], 0
	v_mov_b64_e32 v[14:15], 0
	v_mov_b64_e32 v[20:21], 0
	v_mov_b64_e32 v[22:23], 0
	v_mov_b64_e32 v[28:29], 0
	v_mov_b64_e32 v[30:31], 0
	v_mov_b64_e32 v[36:37], 0
	v_mov_b64_e32 v[38:39], 0
	v_mov_b64_e32 v[44:45], 0
	v_mov_b64_e32 v[46:47], 0
	v_mov_b64_e32 v[52:53], 0
	v_mov_b64_e32 v[54:55], 0
	v_mov_b64_e32 v[8:9], 0
	v_mov_b64_e32 v[10:11], 0
	v_mov_b64_e32 v[16:17], 0
	v_mov_b64_e32 v[18:19], 0
	v_mov_b64_e32 v[24:25], 0
	v_mov_b64_e32 v[26:27], 0
	v_mov_b64_e32 v[32:33], 0
	v_mov_b64_e32 v[34:35], 0
	v_mov_b64_e32 v[40:41], 0
	v_mov_b64_e32 v[42:43], 0
	v_mov_b64_e32 v[48:49], 0
	v_mov_b64_e32 v[50:51], 0
	v_mov_b64_e32 v[56:57], 0
	v_mov_b64_e32 v[58:59], 0
	v_mov_b64_e32 v[60:61], 0
	v_mov_b64_e32 v[62:63], 0
	v_mov_b64_e32 v[64:65], 0
	v_mov_b64_e32 v[66:67], 0
	v_mov_b64_e32 v[68:69], 0
	v_mov_b64_e32 v[70:71], 0
	v_mov_b64_e32 v[76:77], 0
	v_mov_b64_e32 v[78:79], 0
	v_mov_b64_e32 v[84:85], 0
	v_mov_b64_e32 v[86:87], 0
	v_mov_b64_e32 v[92:93], 0
	v_mov_b64_e32 v[94:95], 0
	v_mov_b64_e32 v[100:101], 0
	v_mov_b64_e32 v[102:103], 0
	v_mov_b64_e32 v[108:109], 0
	v_mov_b64_e32 v[110:111], 0
	v_mov_b64_e32 v[116:117], 0
	v_mov_b64_e32 v[118:119], 0
	v_mov_b64_e32 v[72:73], 0
	v_mov_b64_e32 v[74:75], 0
	v_mov_b64_e32 v[80:81], 0
	v_mov_b64_e32 v[82:83], 0
	v_mov_b64_e32 v[88:89], 0
	v_mov_b64_e32 v[90:91], 0
	v_mov_b64_e32 v[96:97], 0
	v_mov_b64_e32 v[98:99], 0
	v_mov_b64_e32 v[104:105], 0
	v_mov_b64_e32 v[106:107], 0
	v_mov_b64_e32 v[112:113], 0
	v_mov_b64_e32 v[114:115], 0
	v_mov_b64_e32 v[120:121], 0
	v_mov_b64_e32 v[122:123], 0
	v_mov_b64_e32 v[124:125], 0
	v_mov_b64_e32 v[126:127], 0

; __device__ __forceinline__ unsigned cvt_pk_bf16(float lo, float hi) { unsigned r; asm volatile("v_cvt_pk_bf16_f32 %0, %1, %2" : "=v"(r) : "v"(lo), "v"(hi)); return r; }
; __device__ __forceinline__ void st16_wt(void* p, u32x4 v) { asm volatile("global_store_dwordx4 %0, %1, off sc1\n\ts_nop 1" :: "v"(p), "v"(v) : "memory"); }
;     __device__ __forceinline__ void operator()(const f32x4 (&acc)[2][2][4][2], const Unit& u, int wr, int wc, int fr, int fq) const {
;     ...
;             for (int m = 0; m < 4; ++m) { bf16_t* rowp = base + (size_t)(row0 + ai * HALF + m * 16) * ldc + col0;
; #pragma unroll
;                 for (int bj = 0; bj < 2; ++bj) { f32x4 v0 = acc[ai][bj][m][0] + bv[bj][0], v1 = acc[ai][bj][m][1] + bv[bj][1];
;                     if (ACT == 1) { f32x2 a = gelu_pk((f32x2){v0[0], v0[1]}), b = gelu_pk((f32x2){v0[2], v0[3]}), c = gelu_pk((f32x2){v1[0], v1[1]}), d = gelu_pk((f32x2){v1[2], v1[3]});
;                         v0 = (f32x4){a.x, a.y, b.x, b.y}; v1 = (f32x4){c.x, c.y, d.x, d.y}; }
;                     v0 = v0 * sc; v1 = v1 * sc; u32x4 w; w.x = cvt_pk_bf16(v0[0], v0[1]); w.y = cvt_pk_bf16(v0[2], v0[3]); w.z = cvt_pk_bf16(v1[0], v1[1]); w.w = cvt_pk_bf16(v1[2], v1[3]);
;                     st16_wt(rowp + bj * HALF, w); } }
.LBB0_160:
	v_lshl_or_b32 v144, s97, 8, v148
	v_ashrrev_i32_e32 v145, 31, v144
	v_lshl_add_u32 v156, s74, 8, v146
	v_lshl_add_u64 v[144:145], v[144:145], 1, s[20:21]
	v_cvt_pk_bf16_f32 v123, v122, v123
	v_cvt_pk_bf16_f32 v122, v120, v121
	v_cvt_pk_bf16_f32 v120, v124, v125
	v_cvt_pk_bf16_f32 v121, v126, v127
	v_mad_i64_i32 v[152:153], s[14:15], v156, s96, v[144:145]
	global_store_dwordx4 v[152:153], v[120:123], off sc1
	s_nop 1
	v_cvt_pk_bf16_f32 v111, v110, v111
	v_cvt_pk_bf16_f32 v110, v108, v109
	v_cvt_pk_bf16_f32 v108, v116, v117
	v_cvt_pk_bf16_f32 v109, v118, v119
	v_lshl_add_u64 v[116:117], v[152:153], 0, s[40:41]
	global_store_dwordx4 v[116:117], v[108:111], off sc1
	s_nop 1
	v_or_b32_e32 v108, 16, v156
	v_cvt_pk_bf16_f32 v107, v106, v107
	v_cvt_pk_bf16_f32 v106, v104, v105
	v_cvt_pk_bf16_f32 v104, v112, v113
	v_cvt_pk_bf16_f32 v105, v114, v115
	v_mad_i64_i32 v[108:109], s[14:15], v108, s96, v[144:145]
	global_store_dwordx4 v[108:109], v[104:107], off sc1
	s_nop 1
	v_cvt_pk_bf16_f32 v95, v94, v95
	v_cvt_pk_bf16_f32 v94, v92, v93
	v_cvt_pk_bf16_f32 v92, v100, v101
	v_cvt_pk_bf16_f32 v93, v102, v103
	v_lshl_add_u64 v[100:101], v[108:109], 0, s[40:41]
	global_store_dwordx4 v[100:101], v[92:95], off sc1
	s_nop 1
	v_or_b32_e32 v92, 32, v156
	v_cvt_pk_bf16_f32 v91, v90, v91
	v_cvt_pk_bf16_f32 v90, v88, v89
	v_cvt_pk_bf16_f32 v88, v96, v97
	v_cvt_pk_bf16_f32 v89, v98, v99
	v_mad_i64_i32 v[92:93], s[14:15], v92, s96, v[144:145]
	global_store_dwordx4 v[92:93], v[88:91], off sc1
	s_nop 1
	v_cvt_pk_bf16_f32 v79, v78, v79
	v_cvt_pk_bf16_f32 v78, v76, v77
	v_cvt_pk_bf16_f32 v76, v84, v85
	v_cvt_pk_bf16_f32 v77, v86, v87
	v_lshl_add_u64 v[84:85], v[92:93], 0, s[40:41]
	global_store_dwordx4 v[84:85], v[76:79], off sc1
	s_nop 1
	v_or_b32_e32 v76, 48, v156
	v_cvt_pk_bf16_f32 v75, v74, v75
	v_cvt_pk_bf16_f32 v74, v72, v73
	v_cvt_pk_bf16_f32 v72, v80, v81
	v_cvt_pk_bf16_f32 v73, v82, v83
	v_mad_i64_i32 v[76:77], s[14:15], v76, s96, v[144:145]
	global_store_dwordx4 v[76:77], v[72:75], off sc1
	s_nop 1
	v_cvt_pk_bf16_f32 v67, v66, v67
	v_cvt_pk_bf16_f32 v66, v64, v65
	v_cvt_pk_bf16_f32 v64, v68, v69
	v_cvt_pk_bf16_f32 v65, v70, v71
	v_lshl_add_u64 v[68:69], v[76:77], 0, s[40:41]
	global_store_dwordx4 v[68:69], v[64:67], off sc1
	s_nop 1
	v_add_u32_e32 v64, 0x80, v156
	v_cvt_pk_bf16_f32 v59, v58, v59
	v_cvt_pk_bf16_f32 v58, v56, v57
	v_cvt_pk_bf16_f32 v56, v60, v61
	v_cvt_pk_bf16_f32 v57, v62, v63
	v_mad_i64_i32 v[64:65], s[14:15], v64, s96, v[144:145]
	global_store_dwordx4 v[64:65], v[56:59], off sc1
	s_nop 1
	v_cvt_pk_bf16_f32 v47, v46, v47
	v_cvt_pk_bf16_f32 v46, v44, v45
	v_cvt_pk_bf16_f32 v44, v52, v53
	v_cvt_pk_bf16_f32 v45, v54, v55
	v_lshl_add_u64 v[52:53], v[64:65], 0, s[40:41]
	global_store_dwordx4 v[52:53], v[44:47], off sc1
	s_nop 1
	v_add_u32_e32 v44, 0x90, v156
	v_cvt_pk_bf16_f32 v43, v42, v43
	v_cvt_pk_bf16_f32 v42, v40, v41
	v_cvt_pk_bf16_f32 v40, v48, v49
	v_cvt_pk_bf16_f32 v41, v50, v51
	v_mad_i64_i32 v[44:45], s[14:15], v44, s96, v[144:145]
	global_store_dwordx4 v[44:45], v[40:43], off sc1
	s_nop 1
	v_cvt_pk_bf16_f32 v31, v30, v31
	v_cvt_pk_bf16_f32 v30, v28, v29
	v_cvt_pk_bf16_f32 v28, v36, v37
	v_cvt_pk_bf16_f32 v29, v38, v39
	v_lshl_add_u64 v[36:37], v[44:45], 0, s[40:41]
	global_store_dwordx4 v[36:37], v[28:31], off sc1
	s_nop 1
	v_add_u32_e32 v28, 0xa0, v156
	v_cvt_pk_bf16_f32 v27, v26, v27
	v_cvt_pk_bf16_f32 v26, v24, v25
	v_cvt_pk_bf16_f32 v24, v32, v33
	v_cvt_pk_bf16_f32 v25, v34, v35
	v_mad_i64_i32 v[28:29], s[14:15], v28, s96, v[144:145]
	global_store_dwordx4 v[28:29], v[24:27], off sc1
	s_nop 1
	v_cvt_pk_bf16_f32 v15, v14, v15
	v_cvt_pk_bf16_f32 v14, v12, v13
	v_cvt_pk_bf16_f32 v12, v20, v21
	v_cvt_pk_bf16_f32 v13, v22, v23
	v_lshl_add_u64 v[20:21], v[28:29], 0, s[40:41]
	global_store_dwordx4 v[20:21], v[12:15], off sc1
	s_nop 1
	v_add_u32_e32 v12, 0xb0, v156
	v_cvt_pk_bf16_f32 v11, v10, v11
	v_cvt_pk_bf16_f32 v10, v8, v9
	v_cvt_pk_bf16_f32 v8, v16, v17
	v_cvt_pk_bf16_f32 v9, v18, v19
	v_mad_i64_i32 v[12:13], s[14:15], v12, s96, v[144:145]
	global_store_dwordx4 v[12:13], v[8:11], off sc1
	s_nop 1
	v_cvt_pk_bf16_f32 v3, v2, v3
	v_cvt_pk_bf16_f32 v2, v0, v1
	v_cvt_pk_bf16_f32 v0, v4, v5
	v_cvt_pk_bf16_f32 v1, v6, v7
	v_lshl_add_u64 v[4:5], v[12:13], 0, s[40:41]
	s_andn2_b64 vcc, exec, s[36:37]
	global_store_dwordx4 v[4:5], v[0:3], off sc1
	s_nop 1
	s_mov_b64 s[18:19], -1
	s_cbranch_vccnz .LBB0_153
	s_andn2_b64 vcc, exec, s[0:1]
	s_cbranch_vccnz .LBB0_152
	s_barrier
	s_branch .LBB0_152

; template <class Epi, class Sched, bool ALIGN_EPI = false, bool SP2 = false>
; __device__ __forceinline__ void gemm_phase(PG8_LAS unsigned char* lds, const Gemm g, const Sched& S, const Epi& E) {
;     ...
;         const bool has_next = S.next(ui + 1, nxt);
;         const char* nA = has_next ? (const char*)g.A + (size_t)nxt.pm * tstep : cA; const char* nB = has_next ? (const char*)g.Bt + (size_t)nxt.pn * tstep : cB;
;     ...
; #pragma unroll
;         for (int a = 0; a < 2; ++a)
; #pragma unroll
;             for (int b = 0; b < 2; ++b)
; #pragma unroll
;                 for (int m = 0; m < 4; ++m)
; #pragma unroll
;                     for (int n = 0; n < 2; ++n) acc[a][b][m][n] = (f32x4){0.f, 0.f, 0.f, 0.f};
;         cur = nxt; cA = nA; cB = nB; ++ui;
.LBB0_541:
	s_ashr_i32 s51, s50, 31
	s_lshl_b64 s[14:15], s[50:51], 19
	s_add_u32 s52, s2, s14
	s_addc_u32 s53, s3, s15
	s_and_b64 s[14:15], s[38:39], exec
	s_cselect_b32 s51, s53, s67
	s_cselect_b32 s89, s52, s66
	s_ashr_i32 s49, s48, 31
	s_lshl_b64 s[14:15], s[48:49], 19
	s_add_u32 s54, s74, s14
	s_addc_u32 s55, s75, s15
	s_and_b64 s[14:15], s[38:39], exec
	s_cselect_b32 s49, s55, s77
	s_cselect_b32 s90, s54, s76
	s_add_u32 s66, s66, 0x40080
	s_addc_u32 s67, s67, 0
	s_add_u32 s76, s76, 0x100
	v_mov_b32_e32 v0, 0
	s_addc_u32 s33, s77, 0
	s_mov_b32 s16, -2
	s_waitcnt lgkmcnt(0)
	v_mov_b32_e32 v1, v0
	v_mov_b64_e32 v[2:3], 0
	v_mov_b64_e32 v[4:5], 0
	v_mov_b64_e32 v[6:7], 0
	v_mov_b64_e32 v[16:17], 0
	v_mov_b64_e32 v[18:19], 0
	v_mov_b64_e32 v[20:21], 0
	v_mov_b64_e32 v[22:23], 0
	v_mov_b64_e32 v[32:33], 0
	v_mov_b64_e32 v[34:35], 0
	s_waitcnt vmcnt(0)
	v_mov_b64_e32 v[36:37], 0
	v_mov_b64_e32 v[38:39], 0
	v_mov_b64_e32 v[48:49], 0
	v_mov_b64_e32 v[50:51], 0
	v_mov_b64_e32 v[52:53], 0
	v_mov_b64_e32 v[54:55], 0
	v_mov_b64_e32 v[8:9], 0
	v_mov_b64_e32 v[10:11], 0
	v_mov_b64_e32 v[12:13], 0
	v_mov_b64_e32 v[14:15], 0
	v_mov_b64_e32 v[24:25], 0
	v_mov_b64_e32 v[26:27], 0
	v_mov_b64_e32 v[28:29], 0
	v_mov_b64_e32 v[30:31], 0
	v_mov_b64_e32 v[40:41], 0
	v_mov_b64_e32 v[42:43], 0
	v_mov_b64_e32 v[44:45], 0
	v_mov_b64_e32 v[46:47], 0
	v_mov_b64_e32 v[56:57], 0
	v_mov_b64_e32 v[58:59], 0
	v_mov_b64_e32 v[60:61], 0
	v_mov_b64_e32 v[62:63], 0
	v_mov_b64_e32 v[64:65], 0
	v_mov_b64_e32 v[66:67], 0
	v_mov_b64_e32 v[68:69], 0
	v_mov_b64_e32 v[70:71], 0
	v_mov_b64_e32 v[96:97], 0
	v_mov_b64_e32 v[98:99], 0
	v_mov_b64_e32 v[100:101], 0
	v_mov_b64_e32 v[102:103], 0
	v_mov_b64_e32 v[112:113], 0
	v_mov_b64_e32 v[114:115], 0
	v_mov_b64_e32 v[116:117], 0
	v_mov_b64_e32 v[118:119], 0
	v_mov_b64_e32 v[128:129], 0
	v_mov_b64_e32 v[130:131], 0
	v_mov_b64_e32 v[132:133], 0
	v_mov_b64_e32 v[134:135], 0
	v_mov_b64_e32 v[80:81], 0
	v_mov_b64_e32 v[82:83], 0
	v_mov_b64_e32 v[84:85], 0
	v_mov_b64_e32 v[86:87], 0
	v_mov_b64_e32 v[104:105], 0
	v_mov_b64_e32 v[106:107], 0
	v_mov_b64_e32 v[108:109], 0
	v_mov_b64_e32 v[110:111], 0
	v_mov_b64_e32 v[120:121], 0
	v_mov_b64_e32 v[122:123], 0
	v_mov_b64_e32 v[124:125], 0
	v_mov_b64_e32 v[126:127], 0
	v_mov_b64_e32 v[136:137], 0
	v_mov_b64_e32 v[138:139], 0
	v_mov_b64_e32 v[140:141], 0
	v_mov_b64_e32 v[142:143], 0

; template <class Epi, class Sched, bool ALIGN_EPI = false, bool SP2 = false>
; __device__ __forceinline__ void gemm_phase(PG8_LAS unsigned char* lds, const Gemm g, const Sched& S, const Epi& E) {
;     ...
;         const bool has_next = S.next(ui + 1, nxt);
;         const char* nA = has_next ? (const char*)g.A + (size_t)nxt.pm * tstep : cA; const char* nB = has_next ? (const char*)g.Bt + (size_t)nxt.pn * tstep : cB;
;     ...
; #pragma unroll
;         for (int a = 0; a < 2; ++a)
; #pragma unroll
;             for (int b = 0; b < 2; ++b)
; #pragma unroll
;                 for (int m = 0; m < 4; ++m)
; #pragma unroll
;                     for (int n = 0; n < 2; ++n) acc[a][b][m][n] = (f32x4){0.f, 0.f, 0.f, 0.f};
;         cur = nxt; cA = nA; cB = nB; ++ui;
.LBB0_636:
	s_ashr_i32 s55, s54, 31
	s_lshl_b64 s[14:15], s[54:55], 19
	s_add_u32 s56, s12, s14
	s_addc_u32 s57, s13, s15
	s_and_b64 s[14:15], s[36:37], exec
	s_cselect_b32 s55, s57, s39
	s_cselect_b32 s68, s56, s38
	s_ashr_i32 s53, s52, 31
	s_lshl_b64 s[14:15], s[52:53], 19
	s_add_u32 s58, s70, s14
	s_addc_u32 s59, s71, s15
	s_and_b64 s[14:15], s[36:37], exec
	s_cselect_b32 s53, s59, s41
	s_cselect_b32 s69, s58, s40
	s_add_u32 s38, s38, 0x40080
	s_addc_u32 s39, s39, 0
	s_add_u32 s72, s40, 0x100
	v_mov_b32_e32 v0, 0
	s_addc_u32 s33, s41, 0
	s_mov_b32 s16, -2
	v_mov_b32_e32 v1, v0
	v_mov_b64_e32 v[2:3], 0
	v_mov_b64_e32 v[4:5], 0
	v_mov_b64_e32 v[6:7], 0
	v_mov_b64_e32 v[16:17], 0
	v_mov_b64_e32 v[18:19], 0
	v_mov_b64_e32 v[20:21], 0
	v_mov_b64_e32 v[22:23], 0
	v_mov_b64_e32 v[32:33], 0
	v_mov_b64_e32 v[34:35], 0
	s_waitcnt vmcnt(0)
	v_mov_b64_e32 v[36:37], 0
	v_mov_b64_e32 v[38:39], 0
	v_mov_b64_e32 v[48:49], 0
	v_mov_b64_e32 v[50:51], 0
	v_mov_b64_e32 v[52:53], 0
	v_mov_b64_e32 v[54:55], 0
	v_mov_b64_e32 v[8:9], 0
	v_mov_b64_e32 v[10:11], 0
	v_mov_b64_e32 v[12:13], 0
	v_mov_b64_e32 v[14:15], 0
	v_mov_b64_e32 v[24:25], 0
	v_mov_b64_e32 v[26:27], 0
	v_mov_b64_e32 v[28:29], 0
	v_mov_b64_e32 v[30:31], 0
	v_mov_b64_e32 v[40:41], 0
	v_mov_b64_e32 v[42:43], 0
	v_mov_b64_e32 v[44:45], 0
	v_mov_b64_e32 v[46:47], 0
	v_mov_b64_e32 v[56:57], 0
	v_mov_b64_e32 v[58:59], 0
	v_mov_b64_e32 v[60:61], 0
	v_mov_b64_e32 v[62:63], 0
	v_mov_b64_e32 v[64:65], 0
	v_mov_b64_e32 v[66:67], 0
	v_mov_b64_e32 v[68:69], 0
	v_mov_b64_e32 v[70:71], 0
	v_mov_b64_e32 v[88:89], 0
	v_mov_b64_e32 v[90:91], 0
	v_mov_b64_e32 v[92:93], 0
	v_mov_b64_e32 v[94:95], 0
	v_mov_b64_e32 v[120:121], 0
	v_mov_b64_e32 v[122:123], 0
	v_mov_b64_e32 v[124:125], 0
	v_mov_b64_e32 v[126:127], 0
	v_mov_b64_e32 v[144:145], 0
	v_mov_b64_e32 v[146:147], 0
	v_mov_b64_e32 v[148:149], 0
	v_mov_b64_e32 v[150:151], 0
	v_mov_b64_e32 v[76:77], 0
	v_mov_b64_e32 v[78:79], 0
	v_mov_b64_e32 v[80:81], 0
	v_mov_b64_e32 v[82:83], 0
	v_mov_b64_e32 v[104:105], 0
	v_mov_b64_e32 v[106:107], 0
	v_mov_b64_e32 v[108:109], 0
	v_mov_b64_e32 v[110:111], 0
	v_mov_b64_e32 v[132:133], 0
	v_mov_b64_e32 v[134:135], 0
	v_mov_b64_e32 v[136:137], 0
	v_mov_b64_e32 v[138:139], 0
	v_mov_b64_e32 v[152:153], 0
	v_mov_b64_e32 v[154:155], 0
	v_mov_b64_e32 v[156:157], 0
	v_mov_b64_e32 v[158:159], 0

; template <class Epi, class Sched, bool ALIGN_EPI = false, bool SP2 = false>
; __device__ __forceinline__ void gemm_phase(PG8_LAS unsigned char* lds, const Gemm g, const Sched& S, const Epi& E) {
;     ...
;         const bool has_next = S.next(ui + 1, nxt);
;         const char* nA = has_next ? (const char*)g.A + (size_t)nxt.pm * tstep : cA; const char* nB = has_next ? (const char*)g.Bt + (size_t)nxt.pn * tstep : cB;
;     ...
; #pragma unroll
;         for (int a = 0; a < 2; ++a)
; #pragma unroll
;             for (int b = 0; b < 2; ++b)
; #pragma unroll
;                 for (int m = 0; m < 4; ++m)
; #pragma unroll
;                     for (int n = 0; n < 2; ++n) acc[a][b][m][n] = (f32x4){0.f, 0.f, 0.f, 0.f};
;         cur = nxt; cA = nA; cB = nB; ++ui;
.LBB0_995:
	s_ashr_i32 s27, s26, 31
	s_lshl_b64 s[28:29], s[26:27], 19
	s_add_u32 s28, s12, s28
	s_addc_u32 s29, s13, s29
	s_and_b64 s[30:31], s[0:1], exec
	s_cselect_b32 s27, s29, s37
	s_cselect_b32 s57, s28, s36
	s_ashr_i32 s25, s24, 31
	s_lshl_b64 s[30:31], s[24:25], 19
	s_add_u32 s30, s66, s30
	s_addc_u32 s31, s67, s31
	s_and_b64 s[40:41], s[0:1], exec
	s_cselect_b32 s25, s31, s39
	s_cselect_b32 s58, s30, s38
	s_add_u32 s36, s36, 0x40080
	s_addc_u32 s37, s37, 0
	s_add_u32 s59, s38, 0x100
	v_mov_b32_e32 v0, 0
	s_addc_u32 s60, s39, 0
	s_mov_b32 s61, -2
	v_mov_b32_e32 v1, v0
	v_mov_b64_e32 v[2:3], 0
	v_mov_b64_e32 v[4:5], 0
	v_mov_b64_e32 v[6:7], 0
	v_mov_b64_e32 v[12:13], 0
	v_mov_b64_e32 v[14:15], 0
	v_mov_b64_e32 v[16:17], 0
	v_mov_b64_e32 v[18:19], 0
	v_mov_b64_e32 v[24:25], 0
	v_mov_b64_e32 v[26:27], 0
	v_mov_b64_e32 v[32:33], 0
	v_mov_b64_e32 v[34:35], 0
	v_mov_b64_e32 v[40:41], 0
	v_mov_b64_e32 v[42:43], 0
	v_mov_b64_e32 v[48:49], 0
	v_mov_b64_e32 v[50:51], 0
	v_mov_b64_e32 v[8:9], 0
	v_mov_b64_e32 v[10:11], 0
	v_mov_b64_e32 v[20:21], 0
	v_mov_b64_e32 v[22:23], 0
	v_mov_b64_e32 v[28:29], 0
	v_mov_b64_e32 v[30:31], 0
	v_mov_b64_e32 v[36:37], 0
	v_mov_b64_e32 v[38:39], 0
	v_mov_b64_e32 v[44:45], 0
	v_mov_b64_e32 v[46:47], 0
	v_mov_b64_e32 v[52:53], 0
	v_mov_b64_e32 v[54:55], 0
	v_mov_b64_e32 v[56:57], 0
	v_mov_b64_e32 v[58:59], 0
	v_mov_b64_e32 v[60:61], 0
	v_mov_b64_e32 v[62:63], 0
	v_mov_b64_e32 v[64:65], 0
	v_mov_b64_e32 v[66:67], 0
	v_mov_b64_e32 v[68:69], 0
	v_mov_b64_e32 v[70:71], 0
	v_mov_b64_e32 v[72:73], 0
	v_mov_b64_e32 v[74:75], 0
	v_mov_b64_e32 v[80:81], 0
	v_mov_b64_e32 v[82:83], 0
	v_mov_b64_e32 v[88:89], 0
	v_mov_b64_e32 v[90:91], 0
	v_mov_b64_e32 v[96:97], 0
	v_mov_b64_e32 v[98:99], 0
	v_mov_b64_e32 v[104:105], 0
	v_mov_b64_e32 v[106:107], 0
	v_mov_b64_e32 v[112:113], 0
	v_mov_b64_e32 v[114:115], 0
	v_mov_b64_e32 v[76:77], 0
	v_mov_b64_e32 v[78:79], 0
	v_mov_b64_e32 v[84:85], 0
	v_mov_b64_e32 v[86:87], 0
	v_mov_b64_e32 v[92:93], 0
	v_mov_b64_e32 v[94:95], 0
	v_mov_b64_e32 v[100:101], 0
	v_mov_b64_e32 v[102:103], 0
	v_mov_b64_e32 v[108:109], 0
	v_mov_b64_e32 v[110:111], 0
	v_mov_b64_e32 v[116:117], 0
	v_mov_b64_e32 v[118:119], 0
	v_mov_b64_e32 v[120:121], 0
	v_mov_b64_e32 v[122:123], 0
	v_mov_b64_e32 v[124:125], 0
	v_mov_b64_e32 v[126:127], 0
